# sel branch: hand-scheduled att_step2 block + single-block fast steps + no phi copies
# speedup vs baseline: 1.0224x; 1.0091x over previous
.LBB0_1323:
	s_and_b32 s23, s9, 1
	s_andn2_b64 vcc, exec, s[0:1]
	s_mul_i32 s1, s23, 0x4800
	s_mul_i32 s0, s23, 0x1800
	s_cbranch_vccnz .LBB0_1330
	s_add_i32 s10, s22, 1
	s_cmp_ge_u32 s10, s20
	s_cbranch_scc1 .Lsel_generic
	v_cmp_neq_f32_e32 vcc, 0, v243
	s_cmp_lg_u64 vcc, 0
	s_cbranch_scc1 .Lsel_generic
	s_cmp_eq_u64 s[6:7], 0
	s_cbranch_scc1 .Lsel_noa
	s_lshr_b32 s6, s9, 2
	s_and_b32 s6, s6, 0x3ffffff8
	s_waitcnt lgkmcnt(0)
	v_add3_u32 v251, s1, v205, v204
	v_add_u32_e32 v16, s6, v209
	s_add_i32 s1, s1, s0
	ds_read_b128 v[50:53], v251
	ds_read_b128 v[54:57], v251 offset:32
	ds_read_b128 v[58:61], v251 offset:64
	ds_read_b128 v[62:65], v251 offset:96
	ds_read_b128 v[66:69], v251 offset:4608
	ds_read_b128 v[70:73], v251 offset:4640
	ds_read_b128 v[74:77], v251 offset:4672
	ds_read_b128 v[78:81], v251 offset:4704
	ds_read_b64 v[16:17], v16
	v_add3_u32 v250, s1, v242, v244
	s_waitcnt lgkmcnt(8)
	v_mfma_f32_32x32x16_bf16 v[146:161], v[50:53], v[114:117], 0
	ds_read_b64_tr_b16 v[212:213], v250 offset:36864
	ds_read_b64_tr_b16 v[214:215], v250 offset:38400
	s_waitcnt lgkmcnt(9)
	v_mfma_f32_32x32x16_bf16 v[146:161], v[54:57], v[118:121], v[146:161]
	ds_read_b64_tr_b16 v[216:217], v250 offset:36928
	ds_read_b64_tr_b16 v[218:219], v250 offset:38464
	s_waitcnt lgkmcnt(10)
	v_mfma_f32_32x32x16_bf16 v[146:161], v[58:61], v[122:125], v[146:161]
	ds_read_b64_tr_b16 v[220:221], v250 offset:39936
	ds_read_b64_tr_b16 v[222:223], v250 offset:41472
	s_waitcnt lgkmcnt(11)
	v_mfma_f32_32x32x16_bf16 v[146:161], v[62:65], v[126:129], v[146:161]
	ds_read_b64_tr_b16 v[224:225], v250 offset:40000
	ds_read_b64_tr_b16 v[226:227], v250 offset:41536
	s_waitcnt lgkmcnt(8)
	v_and_b32_e32 v16, s28, v16
	v_and_b32_e32 v17, s29, v17
	v_cmp_eq_u64_e32 vcc, 0, v[16:17]
	s_nop 2
	v_mfma_f32_32x32x16_bf16 v[162:177], v[66:69], v[114:117], 0
	ds_read_b64_tr_b16 v[228:229], v250 offset:43008
	ds_read_b64_tr_b16 v[230:231], v250 offset:44544
	v_exp_f32_e32 v8, v146
	v_exp_f32_e32 v9, v147
	v_exp_f32_e32 v10, v148
	v_exp_f32_e32 v11, v149
	v_exp_f32_e32 v12, v150
	v_exp_f32_e32 v13, v151
	v_exp_f32_e32 v14, v152
	v_exp_f32_e32 v15, v153
	v_cvt_pk_bf16_f32 v178, v8, v9
	v_cvt_pk_bf16_f32 v179, v10, v11
	v_cvt_pk_bf16_f32 v180, v12, v13
	v_mfma_f32_32x32x16_bf16 v[162:177], v[70:73], v[118:121], v[162:177]
	ds_read_b64_tr_b16 v[232:233], v250 offset:43072
	ds_read_b64_tr_b16 v[234:235], v250 offset:44608
	v_cvt_pk_bf16_f32 v181, v14, v15
	v_add_f32_e32 v8, v8, v9
	v_add_f32_e32 v10, v10, v11
	v_add_f32_e32 v12, v12, v13
	v_add_f32_e32 v14, v14, v15
	v_add_f32_e32 v8, v8, v10
	v_add_f32_e32 v12, v12, v14
	v_add_f32_e32 v202, v8, v12
	v_cndmask_b32_e64 v178, v178, 0, vcc
	v_cndmask_b32_e64 v179, v179, 0, vcc
	v_cndmask_b32_e64 v180, v180, 0, vcc
	v_cndmask_b32_e64 v181, v181, 0, vcc
	v_mfma_f32_32x32x16_bf16 v[162:177], v[74:77], v[122:125], v[162:177]
	ds_read_b64_tr_b16 v[236:237], v250 offset:46080
	ds_read_b64_tr_b16 v[238:239], v250 offset:47616
	v_exp_f32_e32 v8, v154
	v_exp_f32_e32 v9, v155
	v_exp_f32_e32 v10, v156
	v_exp_f32_e32 v11, v157
	v_exp_f32_e32 v12, v158
	v_exp_f32_e32 v13, v159
	v_exp_f32_e32 v14, v160
	v_exp_f32_e32 v15, v161
	v_cvt_pk_bf16_f32 v182, v8, v9
	v_cvt_pk_bf16_f32 v183, v10, v11
	v_cvt_pk_bf16_f32 v184, v12, v13
	v_cvt_pk_bf16_f32 v185, v14, v15
	v_mfma_f32_32x32x16_bf16 v[162:177], v[78:81], v[126:129], v[162:177]
	ds_read_b64_tr_b16 v[4:5], v250 offset:46144
	s_waitcnt lgkmcnt(11)
	ds_read_b64_tr_b16 v[6:7], v250 offset:47680
	v_add_f32_e32 v8, v8, v9
	v_add_f32_e32 v10, v10, v11
	v_add_f32_e32 v12, v12, v13
	v_add_f32_e32 v14, v14, v15
	v_add_f32_e32 v8, v8, v10
	v_add_f32_e32 v12, v12, v14
	v_add_f32_e32 v8, v8, v12
	v_add_f32_e32 v202, v202, v8
	v_cndmask_b32_e64 v182, v182, 0, vcc
	v_cndmask_b32_e64 v183, v183, 0, vcc
	v_cndmask_b32_e64 v184, v184, 0, vcc
	v_cndmask_b32_e64 v185, v185, 0, vcc
	v_mfma_f32_32x32x16_bf16 v[18:33], v[212:215], v[178:181], v[18:33]
	v_exp_f32_e32 v8, v162
	v_exp_f32_e32 v9, v163
	v_exp_f32_e32 v10, v164
	v_exp_f32_e32 v11, v165
	v_exp_f32_e32 v12, v166
	v_exp_f32_e32 v13, v167
	v_exp_f32_e32 v14, v168
	v_exp_f32_e32 v15, v169
	v_cvt_pk_bf16_f32 v186, v8, v9
	v_cvt_pk_bf16_f32 v187, v10, v11
	v_cvt_pk_bf16_f32 v188, v12, v13
	v_cvt_pk_bf16_f32 v189, v14, v15
	v_mfma_f32_32x32x16_bf16 v[34:49], v[216:219], v[178:181], v[34:49]
	v_add_f32_e32 v8, v8, v9
	v_add_f32_e32 v10, v10, v11
	v_add_f32_e32 v12, v12, v13
	v_add_f32_e32 v14, v14, v15
	v_add_f32_e32 v8, v8, v10
	v_add_f32_e32 v12, v12, v14
	v_add_f32_e32 v8, v8, v12
	v_add_f32_e32 v202, v202, v8
	v_cndmask_b32_e64 v186, v186, 0, vcc
	v_cndmask_b32_e64 v187, v187, 0, vcc
	v_cndmask_b32_e64 v188, v188, 0, vcc
	v_cndmask_b32_e64 v189, v189, 0, vcc
	s_waitcnt lgkmcnt(10)
	v_mfma_f32_32x32x16_bf16 v[18:33], v[220:223], v[182:185], v[18:33]
	v_exp_f32_e32 v8, v170
	v_exp_f32_e32 v9, v171
	v_exp_f32_e32 v10, v172
	v_exp_f32_e32 v11, v173
	v_exp_f32_e32 v12, v174
	v_exp_f32_e32 v13, v175
	v_exp_f32_e32 v14, v176
	v_exp_f32_e32 v15, v177
	v_cvt_pk_bf16_f32 v190, v8, v9
	v_cvt_pk_bf16_f32 v191, v10, v11
	v_cvt_pk_bf16_f32 v192, v12, v13
	v_cvt_pk_bf16_f32 v193, v14, v15
	s_waitcnt lgkmcnt(8)
	v_mfma_f32_32x32x16_bf16 v[34:49], v[224:227], v[182:185], v[34:49]
	v_add_f32_e32 v8, v8, v9
	v_add_f32_e32 v10, v10, v11
	v_add_f32_e32 v12, v12, v13
	v_add_f32_e32 v14, v14, v15
	v_add_f32_e32 v8, v8, v10
	v_add_f32_e32 v12, v12, v14
	v_add_f32_e32 v8, v8, v12
	v_add_f32_e32 v202, v202, v8
	v_cndmask_b32_e64 v190, v190, 0, vcc
	v_cndmask_b32_e64 v191, v191, 0, vcc
	v_cndmask_b32_e64 v192, v192, 0, vcc
	v_cndmask_b32_e64 v193, v193, 0, vcc
	s_waitcnt lgkmcnt(6)
	v_mfma_f32_32x32x16_bf16 v[18:33], v[228:231], v[186:189], v[18:33]
	v_cndmask_b32_e64 v202, v202, 0, vcc
	v_add_f32_e32 v252, v2, v202
	v_mov_b32_e32 v2, v252
	s_waitcnt lgkmcnt(4)
	v_mfma_f32_32x32x16_bf16 v[34:49], v[232:235], v[186:189], v[34:49]
	v_mov_b32_e32 v16, v252
	s_nop 1
	s_waitcnt lgkmcnt(2)
	v_mfma_f32_32x32x16_bf16 v[18:33], v[236:239], v[190:193], v[18:33]
	v_permlane32_swap_b32_e32 v2, v16
	v_max_f32_e32 v16, v16, v16
	s_waitcnt lgkmcnt(0)
	v_mfma_f32_32x32x16_bf16 v[34:49], v[4:7], v[190:193], v[34:49]
	v_max_f32_e32 v2, v2, v2
	v_max_f32_e32 v2, v2, v16
	v_cmp_lt_f32_e32 vcc, s15, v2
	s_cbranch_vccnz .Lsel_shift
	s_branch .LBB0_1333
.Lsel_noa:
	s_cmp_eq_u64 s[34:35], 0
	s_cbranch_scc1 .Lsel_none
	s_lshr_b32 s6, s9, 2
	s_and_b32 s6, s6, 0x3ffffff8
	s_waitcnt lgkmcnt(0)
	v_add3_u32 v251, s1, v205, v204
	v_add_u32_e32 v16, s6, v209
	s_add_i32 s1, s1, s0
	ds_read_b128 v[50:53], v251 offset:9216
	ds_read_b128 v[54:57], v251 offset:9248
	ds_read_b128 v[58:61], v251 offset:9280
	ds_read_b128 v[62:65], v251 offset:9312
	ds_read_b128 v[66:69], v251 offset:13824
	ds_read_b128 v[70:73], v251 offset:13856
	ds_read_b128 v[74:77], v251 offset:13888
	ds_read_b128 v[78:81], v251 offset:13920
	ds_read_b64 v[16:17], v16
	v_add3_u32 v250, s1, v242, v244
	s_waitcnt lgkmcnt(8)
	v_mfma_f32_32x32x16_bf16 v[146:161], v[50:53], v[114:117], 0
	ds_read_b64_tr_b16 v[212:213], v250 offset:49152
	ds_read_b64_tr_b16 v[214:215], v250 offset:50688
	s_waitcnt lgkmcnt(9)
	v_mfma_f32_32x32x16_bf16 v[146:161], v[54:57], v[118:121], v[146:161]
	ds_read_b64_tr_b16 v[216:217], v250 offset:49216
	ds_read_b64_tr_b16 v[218:219], v250 offset:50752
	s_waitcnt lgkmcnt(10)
	v_mfma_f32_32x32x16_bf16 v[146:161], v[58:61], v[122:125], v[146:161]
	ds_read_b64_tr_b16 v[220:221], v250 offset:52224
	ds_read_b64_tr_b16 v[222:223], v250 offset:53760
	s_waitcnt lgkmcnt(11)
	v_mfma_f32_32x32x16_bf16 v[146:161], v[62:65], v[126:129], v[146:161]
	ds_read_b64_tr_b16 v[224:225], v250 offset:52288
	ds_read_b64_tr_b16 v[226:227], v250 offset:53824
	s_waitcnt lgkmcnt(8)
	v_and_b32_e32 v16, s26, v16
	v_and_b32_e32 v17, s27, v17
	v_cmp_eq_u64_e32 vcc, 0, v[16:17]
	s_nop 2
	v_mfma_f32_32x32x16_bf16 v[162:177], v[66:69], v[114:117], 0
	ds_read_b64_tr_b16 v[228:229], v250 offset:55296
	ds_read_b64_tr_b16 v[230:231], v250 offset:56832
	v_exp_f32_e32 v8, v146
	v_exp_f32_e32 v9, v147
	v_exp_f32_e32 v10, v148
	v_exp_f32_e32 v11, v149
	v_exp_f32_e32 v12, v150
	v_exp_f32_e32 v13, v151
	v_exp_f32_e32 v14, v152
	v_exp_f32_e32 v15, v153
	v_cvt_pk_bf16_f32 v178, v8, v9
	v_cvt_pk_bf16_f32 v179, v10, v11
	v_cvt_pk_bf16_f32 v180, v12, v13
	v_mfma_f32_32x32x16_bf16 v[162:177], v[70:73], v[118:121], v[162:177]
	ds_read_b64_tr_b16 v[232:233], v250 offset:55360
	ds_read_b64_tr_b16 v[234:235], v250 offset:56896
	v_cvt_pk_bf16_f32 v181, v14, v15
	v_add_f32_e32 v8, v8, v9
	v_add_f32_e32 v10, v10, v11
	v_add_f32_e32 v12, v12, v13
	v_add_f32_e32 v14, v14, v15
	v_add_f32_e32 v8, v8, v10
	v_add_f32_e32 v12, v12, v14
	v_add_f32_e32 v202, v8, v12
	v_cndmask_b32_e64 v178, v178, 0, vcc
	v_cndmask_b32_e64 v179, v179, 0, vcc
	v_cndmask_b32_e64 v180, v180, 0, vcc
	v_cndmask_b32_e64 v181, v181, 0, vcc
	v_mfma_f32_32x32x16_bf16 v[162:177], v[74:77], v[122:125], v[162:177]
	ds_read_b64_tr_b16 v[236:237], v250 offset:58368
	ds_read_b64_tr_b16 v[238:239], v250 offset:59904
	v_exp_f32_e32 v8, v154
	v_exp_f32_e32 v9, v155
	v_exp_f32_e32 v10, v156
	v_exp_f32_e32 v11, v157
	v_exp_f32_e32 v12, v158
	v_exp_f32_e32 v13, v159
	v_exp_f32_e32 v14, v160
	v_exp_f32_e32 v15, v161
	v_cvt_pk_bf16_f32 v182, v8, v9
	v_cvt_pk_bf16_f32 v183, v10, v11
	v_cvt_pk_bf16_f32 v184, v12, v13
	v_cvt_pk_bf16_f32 v185, v14, v15
	v_mfma_f32_32x32x16_bf16 v[162:177], v[78:81], v[126:129], v[162:177]
	ds_read_b64_tr_b16 v[4:5], v250 offset:58432
	s_waitcnt lgkmcnt(11)
	ds_read_b64_tr_b16 v[6:7], v250 offset:59968
	v_add_f32_e32 v8, v8, v9
	v_add_f32_e32 v10, v10, v11
	v_add_f32_e32 v12, v12, v13
	v_add_f32_e32 v14, v14, v15
	v_add_f32_e32 v8, v8, v10
	v_add_f32_e32 v12, v12, v14
	v_add_f32_e32 v8, v8, v12
	v_add_f32_e32 v202, v202, v8
	v_cndmask_b32_e64 v182, v182, 0, vcc
	v_cndmask_b32_e64 v183, v183, 0, vcc
	v_cndmask_b32_e64 v184, v184, 0, vcc
	v_cndmask_b32_e64 v185, v185, 0, vcc
	v_mfma_f32_32x32x16_bf16 v[18:33], v[212:215], v[178:181], v[18:33]
	v_exp_f32_e32 v8, v162
	v_exp_f32_e32 v9, v163
	v_exp_f32_e32 v10, v164
	v_exp_f32_e32 v11, v165
	v_exp_f32_e32 v12, v166
	v_exp_f32_e32 v13, v167
	v_exp_f32_e32 v14, v168
	v_exp_f32_e32 v15, v169
	v_cvt_pk_bf16_f32 v186, v8, v9
	v_cvt_pk_bf16_f32 v187, v10, v11
	v_cvt_pk_bf16_f32 v188, v12, v13
	v_cvt_pk_bf16_f32 v189, v14, v15
	v_mfma_f32_32x32x16_bf16 v[34:49], v[216:219], v[178:181], v[34:49]
	v_add_f32_e32 v8, v8, v9
	v_add_f32_e32 v10, v10, v11
	v_add_f32_e32 v12, v12, v13
	v_add_f32_e32 v14, v14, v15
	v_add_f32_e32 v8, v8, v10
	v_add_f32_e32 v12, v12, v14
	v_add_f32_e32 v8, v8, v12
	v_add_f32_e32 v202, v202, v8
	v_cndmask_b32_e64 v186, v186, 0, vcc
	v_cndmask_b32_e64 v187, v187, 0, vcc
	v_cndmask_b32_e64 v188, v188, 0, vcc
	v_cndmask_b32_e64 v189, v189, 0, vcc
	s_waitcnt lgkmcnt(10)
	v_mfma_f32_32x32x16_bf16 v[18:33], v[220:223], v[182:185], v[18:33]
	v_exp_f32_e32 v8, v170
	v_exp_f32_e32 v9, v171
	v_exp_f32_e32 v10, v172
	v_exp_f32_e32 v11, v173
	v_exp_f32_e32 v12, v174
	v_exp_f32_e32 v13, v175
	v_exp_f32_e32 v14, v176
	v_exp_f32_e32 v15, v177
	v_cvt_pk_bf16_f32 v190, v8, v9
	v_cvt_pk_bf16_f32 v191, v10, v11
	v_cvt_pk_bf16_f32 v192, v12, v13
	v_cvt_pk_bf16_f32 v193, v14, v15
	s_waitcnt lgkmcnt(8)
	v_mfma_f32_32x32x16_bf16 v[34:49], v[224:227], v[182:185], v[34:49]
	v_add_f32_e32 v8, v8, v9
	v_add_f32_e32 v10, v10, v11
	v_add_f32_e32 v12, v12, v13
	v_add_f32_e32 v14, v14, v15
	v_add_f32_e32 v8, v8, v10
	v_add_f32_e32 v12, v12, v14
	v_add_f32_e32 v8, v8, v12
	v_add_f32_e32 v202, v202, v8
	v_cndmask_b32_e64 v190, v190, 0, vcc
	v_cndmask_b32_e64 v191, v191, 0, vcc
	v_cndmask_b32_e64 v192, v192, 0, vcc
	v_cndmask_b32_e64 v193, v193, 0, vcc
	s_waitcnt lgkmcnt(6)
	v_mfma_f32_32x32x16_bf16 v[18:33], v[228:231], v[186:189], v[18:33]
	v_cndmask_b32_e64 v202, v202, 0, vcc
	v_add_f32_e32 v252, v2, v202
	v_mov_b32_e32 v2, v252
	s_waitcnt lgkmcnt(4)
	v_mfma_f32_32x32x16_bf16 v[34:49], v[232:235], v[186:189], v[34:49]
	v_mov_b32_e32 v16, v252
	s_nop 1
	s_waitcnt lgkmcnt(2)
	v_mfma_f32_32x32x16_bf16 v[18:33], v[236:239], v[190:193], v[18:33]
	v_permlane32_swap_b32_e32 v2, v16
	v_max_f32_e32 v16, v16, v16
	s_waitcnt lgkmcnt(0)
	v_mfma_f32_32x32x16_bf16 v[34:49], v[4:7], v[190:193], v[34:49]
	v_max_f32_e32 v2, v2, v2
	v_max_f32_e32 v2, v2, v16
	v_cmp_lt_f32_e32 vcc, s15, v2
	s_cbranch_vccnz .Lsel_shift
	s_branch .LBB0_1333
.Lsel_none:
	v_mov_b32_e32 v252, v2
	s_branch .LBB0_1333
.Lsel_generic:
	s_lshr_b32 s10, s9, 2
	s_add_i32 s14, s1, 0
	s_and_b32 s10, s10, 0x3ffffff8
	s_add_i32 s15, s14, s0
	s_cmp_gt_u32 s22, s20
	v_add_u32_e32 v197, s10, v209
	s_cselect_b64 s[10:11], -1, 0
	s_cmp_eq_u64 s[6:7], 0
	s_cselect_b64 s[6:7], -1, 0
	s_or_b64 s[6:7], s[10:11], s[6:7]
	v_add_u32_e32 v4, s15, v242
	v_mov_b64_e32 v[80:81], v[48:49]
	v_mov_b64_e32 v[64:65], v[32:33]
	s_and_b64 vcc, exec, s[6:7]
	v_add3_u32 v196, s14, v205, v204
	s_mov_b32 s15, 0x49800000
	v_add_u32_e32 v251, v4, v244
	v_mov_b32_e32 v252, v2
	v_mov_b32_e32 v250, v243
	v_mov_b64_e32 v[78:79], v[46:47]
	v_mov_b64_e32 v[76:77], v[44:45]
	v_mov_b64_e32 v[74:75], v[42:43]
	v_mov_b64_e32 v[72:73], v[40:41]
	v_mov_b64_e32 v[70:71], v[38:39]
	v_mov_b64_e32 v[68:69], v[36:37]
	v_mov_b64_e32 v[66:67], v[34:35]
	v_mov_b64_e32 v[62:63], v[30:31]
	v_mov_b64_e32 v[60:61], v[28:29]
	v_mov_b64_e32 v[58:59], v[26:27]
	v_mov_b64_e32 v[56:57], v[24:25]
	v_mov_b64_e32 v[54:55], v[22:23]
	v_mov_b64_e32 v[52:53], v[20:21]
	v_mov_b64_e32 v[50:51], v[18:19]
	s_cbranch_vccnz .LBB0_1342
	ds_read_b64 v[4:5], v197
	ds_read_b128 v[90:93], v196
	ds_read_b128 v[12:15], v196 offset:32
	ds_read_b128 v[8:11], v196 offset:64
	s_cmp_lg_u32 s20, s22
	s_waitcnt lgkmcnt(3)
	v_and_b32_e32 v17, s29, v5
	v_and_b32_e32 v16, s28, v4
	ds_read_b128 v[94:97], v196 offset:4640
	ds_read_b128 v[82:85], v196 offset:4672
	ds_read_b128 v[98:101], v196 offset:4608
	ds_read_b128 v[86:89], v196 offset:96
	ds_read_b128 v[4:7], v196 offset:4704
	v_cmp_ne_u64_e64 s[6:7], 0, v[16:17]
	s_mov_b64 s[10:11], -1
	v_cmp_neq_f32_e32 vcc, 0, v243
	s_cbranch_scc0 .LBB0_1336
	ds_read_b64_tr_b16 v[150:151], v251 offset:36864
	ds_read_b64_tr_b16 v[152:153], v251 offset:38400
	ds_read_b64_tr_b16 v[112:113], v251 offset:38464
	ds_read_b64_tr_b16 v[110:111], v251 offset:36928
	ds_read_b64_tr_b16 v[106:107], v251 offset:39936
	ds_read_b64_tr_b16 v[108:109], v251 offset:41472
	ds_read_b64_tr_b16 v[104:105], v251 offset:41536
	ds_read_b64_tr_b16 v[102:103], v251 offset:40000
	s_waitcnt lgkmcnt(14)
	v_mfma_f32_32x32x16_bf16 v[66:81], v[90:93], v[114:117], 0
	s_waitcnt lgkmcnt(10)
	v_mfma_f32_32x32x16_bf16 v[50:65], v[98:101], v[114:117], 0
	v_mfma_f32_32x32x16_bf16 v[66:81], v[12:15], v[118:121], v[66:81]
	v_mfma_f32_32x32x16_bf16 v[50:65], v[94:97], v[118:121], v[50:65]
	v_mfma_f32_32x32x16_bf16 v[66:81], v[8:11], v[122:125], v[66:81]
	v_mfma_f32_32x32x16_bf16 v[50:65], v[82:85], v[122:125], v[50:65]
	s_waitcnt lgkmcnt(9)
	v_mfma_f32_32x32x16_bf16 v[66:81], v[86:89], v[126:129], v[66:81]
	s_waitcnt lgkmcnt(8)
	v_mfma_f32_32x32x16_bf16 v[50:65], v[4:7], v[126:129], v[50:65]
	s_mov_b64 vcc, vcc
	s_cbranch_vccz .LBB0_1328
	s_nop 7
	v_sub_f32_e32 v81, v81, v243
	v_sub_f32_e32 v80, v80, v243
	v_sub_f32_e32 v79, v79, v243
	v_sub_f32_e32 v78, v78, v243
	v_sub_f32_e32 v77, v77, v243
	v_sub_f32_e32 v76, v76, v243
	v_sub_f32_e32 v75, v75, v243
	v_sub_f32_e32 v74, v74, v243
	v_sub_f32_e32 v73, v73, v243
	v_sub_f32_e32 v72, v72, v243
	v_sub_f32_e32 v71, v71, v243
	v_sub_f32_e32 v70, v70, v243
	v_sub_f32_e32 v69, v69, v243
	v_sub_f32_e32 v68, v68, v243
	v_sub_f32_e32 v67, v67, v243
	v_sub_f32_e32 v66, v66, v243
	v_sub_f32_e32 v65, v65, v243
	v_sub_f32_e32 v64, v64, v243
	v_sub_f32_e32 v63, v63, v243
	v_sub_f32_e32 v62, v62, v243
	v_sub_f32_e32 v61, v61, v243
	v_sub_f32_e32 v60, v60, v243
	v_sub_f32_e32 v59, v59, v243
	v_sub_f32_e32 v58, v58, v243
	v_sub_f32_e32 v57, v57, v243
	v_sub_f32_e32 v56, v56, v243
	v_sub_f32_e32 v55, v55, v243
	v_sub_f32_e32 v54, v54, v243
	v_sub_f32_e32 v53, v53, v243
	v_sub_f32_e32 v52, v52, v243
	v_sub_f32_e32 v51, v51, v243
	v_sub_f32_e32 v50, v50, v243

.LBB0_1330:
	s_and_b64 vcc, exec, s[10:11]
	s_cbranch_vccz .LBB0_1358
	s_lshr_b32 s6, s9, 2
	s_and_b32 s6, s6, 0x3ffffff8
	s_waitcnt lgkmcnt(0)
	v_add3_u32 v251, s1, v205, v204
	v_add_u32_e32 v16, s6, v209
	s_add_i32 s1, s1, s0
	ds_read_b128 v[50:53], v251
	ds_read_b128 v[54:57], v251 offset:32
	ds_read_b128 v[58:61], v251 offset:64
	ds_read_b128 v[62:65], v251 offset:96
	ds_read_b128 v[66:69], v251 offset:4608
	ds_read_b128 v[70:73], v251 offset:4640
	ds_read_b128 v[74:77], v251 offset:4672
	ds_read_b128 v[78:81], v251 offset:4704
	ds_read_b64 v[16:17], v16
	v_add3_u32 v250, s1, v242, v244
	s_waitcnt lgkmcnt(8)
	v_mfma_f32_32x32x16_bf16 v[146:161], v[50:53], v[114:117], 0
	ds_read_b128 v[82:85], v251 offset:9216
	ds_read_b128 v[86:89], v251 offset:9248
	s_waitcnt lgkmcnt(9)
	v_mfma_f32_32x32x16_bf16 v[146:161], v[54:57], v[118:121], v[146:161]
	ds_read_b128 v[90:93], v251 offset:9280
	ds_read_b128 v[94:97], v251 offset:9312
	s_waitcnt lgkmcnt(10)
	v_mfma_f32_32x32x16_bf16 v[146:161], v[58:61], v[122:125], v[146:161]
	ds_read_b128 v[98:101], v251 offset:13824
	ds_read_b128 v[102:105], v251 offset:13856
	s_waitcnt lgkmcnt(11)
	v_mfma_f32_32x32x16_bf16 v[146:161], v[62:65], v[126:129], v[146:161]
	ds_read_b128 v[106:109], v251 offset:13888
	ds_read_b128 v[110:113], v251 offset:13920
	s_waitcnt lgkmcnt(8)
	v_and_b32_e32 v240, s28, v16
	v_and_b32_e32 v241, s29, v17
	v_and_b32_e32 v16, s26, v16
	v_and_b32_e32 v17, s27, v17
	v_cmp_eq_u64_e32 vcc, 0, v[240:241]
	v_cmp_eq_u64_e64 s[6:7], 0, v[16:17]
	v_mfma_f32_32x32x16_bf16 v[162:177], v[66:69], v[114:117], 0
	ds_read_b64_tr_b16 v[212:213], v250 offset:36864
	ds_read_b64_tr_b16 v[214:215], v250 offset:38400
	v_exp_f32_e32 v8, v146
	v_exp_f32_e32 v9, v147
	v_exp_f32_e32 v10, v148
	v_exp_f32_e32 v11, v149
	v_exp_f32_e32 v12, v150
	v_exp_f32_e32 v13, v151
	v_exp_f32_e32 v14, v152
	v_mfma_f32_32x32x16_bf16 v[162:177], v[70:73], v[118:121], v[162:177]
	ds_read_b64_tr_b16 v[216:217], v250 offset:36928
	ds_read_b64_tr_b16 v[218:219], v250 offset:38464
	v_exp_f32_e32 v15, v153
	v_cvt_pk_bf16_f32 v178, v8, v9
	v_cvt_pk_bf16_f32 v179, v10, v11
	v_cvt_pk_bf16_f32 v180, v12, v13
	v_cvt_pk_bf16_f32 v181, v14, v15
	v_add_f32_e32 v8, v8, v9
	v_add_f32_e32 v10, v10, v11
	v_add_f32_e32 v12, v12, v13
	v_mfma_f32_32x32x16_bf16 v[162:177], v[74:77], v[122:125], v[162:177]
	ds_read_b64_tr_b16 v[220:221], v250 offset:39936
	ds_read_b64_tr_b16 v[222:223], v250 offset:41472
	v_add_f32_e32 v14, v14, v15
	v_add_f32_e32 v8, v8, v10
	v_add_f32_e32 v12, v12, v14
	v_add_f32_e32 v202, v8, v12
	v_cndmask_b32_e64 v178, v178, 0, vcc
	v_cndmask_b32_e64 v179, v179, 0, vcc
	v_cndmask_b32_e64 v180, v180, 0, vcc
	v_cndmask_b32_e64 v181, v181, 0, vcc
	v_mfma_f32_32x32x16_bf16 v[162:177], v[78:81], v[126:129], v[162:177]
	ds_read_b64_tr_b16 v[224:225], v250 offset:40000
	s_waitcnt lgkmcnt(11)
	ds_read_b64_tr_b16 v[226:227], v250 offset:41536
	v_exp_f32_e32 v8, v154
	v_exp_f32_e32 v9, v155
	v_exp_f32_e32 v10, v156
	v_exp_f32_e32 v11, v157
	v_exp_f32_e32 v12, v158
	v_exp_f32_e32 v13, v159
	v_exp_f32_e32 v14, v160
	v_exp_f32_e32 v15, v161
	v_mfma_f32_32x32x16_bf16 v[50:65], v[82:85], v[114:117], 0
	ds_read_b64_tr_b16 v[228:229], v250 offset:43008
	ds_read_b64_tr_b16 v[230:231], v250 offset:44544
	v_cvt_pk_bf16_f32 v182, v8, v9
	v_cvt_pk_bf16_f32 v183, v10, v11
	v_cvt_pk_bf16_f32 v184, v12, v13
	v_cvt_pk_bf16_f32 v185, v14, v15
	v_add_f32_e32 v8, v8, v9
	v_add_f32_e32 v10, v10, v11
	v_add_f32_e32 v12, v12, v13
	v_add_f32_e32 v14, v14, v15
	v_mfma_f32_32x32x16_bf16 v[50:65], v[86:89], v[118:121], v[50:65]
	ds_read_b64_tr_b16 v[232:233], v250 offset:43072
	s_waitcnt lgkmcnt(11)
	ds_read_b64_tr_b16 v[234:235], v250 offset:44608
	v_add_f32_e32 v8, v8, v10
	v_add_f32_e32 v12, v12, v14
	v_add_f32_e32 v8, v8, v12
	v_add_f32_e32 v202, v202, v8
	v_cndmask_b32_e64 v182, v182, 0, vcc
	v_cndmask_b32_e64 v183, v183, 0, vcc
	v_cndmask_b32_e64 v184, v184, 0, vcc
	v_cndmask_b32_e64 v185, v185, 0, vcc
	v_mfma_f32_32x32x16_bf16 v[50:65], v[90:93], v[122:125], v[50:65]
	ds_read_b64_tr_b16 v[236:237], v250 offset:46080
	ds_read_b64_tr_b16 v[238:239], v250 offset:47616
	v_exp_f32_e32 v8, v162
	v_exp_f32_e32 v9, v163
	v_exp_f32_e32 v10, v164
	v_exp_f32_e32 v11, v165
	v_exp_f32_e32 v12, v166
	v_exp_f32_e32 v13, v167
	v_exp_f32_e32 v14, v168
	v_exp_f32_e32 v15, v169
	v_mfma_f32_32x32x16_bf16 v[50:65], v[94:97], v[126:129], v[50:65]
	ds_read_b64_tr_b16 v[4:5], v250 offset:46144
	s_waitcnt lgkmcnt(11)
	ds_read_b64_tr_b16 v[6:7], v250 offset:47680
	v_cvt_pk_bf16_f32 v186, v8, v9
	v_cvt_pk_bf16_f32 v187, v10, v11
	v_cvt_pk_bf16_f32 v188, v12, v13
	v_cvt_pk_bf16_f32 v189, v14, v15
	v_add_f32_e32 v8, v8, v9
	v_add_f32_e32 v10, v10, v11
	v_add_f32_e32 v12, v12, v13
	v_add_f32_e32 v14, v14, v15
	v_mfma_f32_32x32x16_bf16 v[66:81], v[98:101], v[114:117], 0
	ds_read_b64_tr_b16 v[146:147], v250 offset:49152
	ds_read_b64_tr_b16 v[148:149], v250 offset:50688
	v_add_f32_e32 v8, v8, v10
	v_add_f32_e32 v12, v12, v14
	v_add_f32_e32 v8, v8, v12
	v_add_f32_e32 v202, v202, v8
	v_cndmask_b32_e64 v186, v186, 0, vcc
	v_cndmask_b32_e64 v187, v187, 0, vcc
	v_cndmask_b32_e64 v188, v188, 0, vcc
	v_cndmask_b32_e64 v189, v189, 0, vcc
	v_mfma_f32_32x32x16_bf16 v[66:81], v[102:105], v[118:121], v[66:81]
	ds_read_b64_tr_b16 v[150:151], v250 offset:49216
	s_waitcnt lgkmcnt(11)
	ds_read_b64_tr_b16 v[152:153], v250 offset:50752
	v_exp_f32_e32 v8, v170
	v_exp_f32_e32 v9, v171
	v_exp_f32_e32 v10, v172
	v_exp_f32_e32 v11, v173
	v_exp_f32_e32 v12, v174
	v_exp_f32_e32 v13, v175
	v_exp_f32_e32 v14, v176
	v_exp_f32_e32 v15, v177
	v_mfma_f32_32x32x16_bf16 v[66:81], v[106:109], v[122:125], v[66:81]
	ds_read_b64_tr_b16 v[154:155], v250 offset:52224
	ds_read_b64_tr_b16 v[156:157], v250 offset:53760
	v_cvt_pk_bf16_f32 v190, v8, v9
	v_cvt_pk_bf16_f32 v191, v10, v11
	v_cvt_pk_bf16_f32 v192, v12, v13
	v_cvt_pk_bf16_f32 v193, v14, v15
	v_add_f32_e32 v8, v8, v9
	v_add_f32_e32 v10, v10, v11
	v_add_f32_e32 v12, v12, v13
	v_add_f32_e32 v14, v14, v15
	v_mfma_f32_32x32x16_bf16 v[66:81], v[110:113], v[126:129], v[66:81]
	ds_read_b64_tr_b16 v[158:159], v250 offset:52288
	s_waitcnt lgkmcnt(11)
	ds_read_b64_tr_b16 v[160:161], v250 offset:53824
	v_add_f32_e32 v8, v8, v10
	v_add_f32_e32 v12, v12, v14
	v_add_f32_e32 v8, v8, v12
	v_add_f32_e32 v202, v202, v8
	v_cndmask_b32_e64 v190, v190, 0, vcc
	v_cndmask_b32_e64 v191, v191, 0, vcc
	v_cndmask_b32_e64 v192, v192, 0, vcc
	v_cndmask_b32_e64 v193, v193, 0, vcc
	v_mfma_f32_32x32x16_bf16 v[18:33], v[212:215], v[178:181], v[18:33]
	v_exp_f32_e32 v8, v50
	v_exp_f32_e32 v9, v51
	v_exp_f32_e32 v10, v52
	v_exp_f32_e32 v11, v53
	v_exp_f32_e32 v12, v54
	v_exp_f32_e32 v13, v55
	v_exp_f32_e32 v14, v56
	v_exp_f32_e32 v15, v57
	v_mfma_f32_32x32x16_bf16 v[34:49], v[216:219], v[178:181], v[34:49]
	ds_read_b64_tr_b16 v[162:163], v250 offset:55296
	ds_read_b64_tr_b16 v[164:165], v250 offset:56832
	v_cvt_pk_bf16_f32 v178, v8, v9
	v_cvt_pk_bf16_f32 v179, v10, v11
	v_cvt_pk_bf16_f32 v180, v12, v13
	v_cvt_pk_bf16_f32 v181, v14, v15
	v_add_f32_e32 v8, v8, v9
	v_add_f32_e32 v10, v10, v11
	v_add_f32_e32 v12, v12, v13
	v_add_f32_e32 v14, v14, v15
	v_mfma_f32_32x32x16_bf16 v[18:33], v[220:223], v[182:185], v[18:33]
	ds_read_b64_tr_b16 v[166:167], v250 offset:55360
	s_waitcnt lgkmcnt(11)
	ds_read_b64_tr_b16 v[168:169], v250 offset:56896
	v_add_f32_e32 v8, v8, v10
	v_add_f32_e32 v12, v12, v14
	v_add_f32_e32 v203, v8, v12
	v_cndmask_b32_e64 v178, v178, 0, s[6:7]
	v_cndmask_b32_e64 v179, v179, 0, s[6:7]
	v_cndmask_b32_e64 v180, v180, 0, s[6:7]
	v_cndmask_b32_e64 v181, v181, 0, s[6:7]
	v_exp_f32_e32 v8, v58
	v_mfma_f32_32x32x16_bf16 v[34:49], v[224:227], v[182:185], v[34:49]
	ds_read_b64_tr_b16 v[170:171], v250 offset:58368
	ds_read_b64_tr_b16 v[172:173], v250 offset:59904
	v_exp_f32_e32 v9, v59
	v_exp_f32_e32 v10, v60
	v_exp_f32_e32 v11, v61
	v_exp_f32_e32 v12, v62
	v_exp_f32_e32 v13, v63
	v_exp_f32_e32 v14, v64
	v_exp_f32_e32 v15, v65
	v_cvt_pk_bf16_f32 v182, v8, v9
	v_mfma_f32_32x32x16_bf16 v[18:33], v[228:231], v[186:189], v[18:33]
	ds_read_b64_tr_b16 v[174:175], v250 offset:58432
	s_waitcnt lgkmcnt(11)
	ds_read_b64_tr_b16 v[176:177], v250 offset:59968
	v_cvt_pk_bf16_f32 v183, v10, v11
	v_cvt_pk_bf16_f32 v184, v12, v13
	v_cvt_pk_bf16_f32 v185, v14, v15
	v_add_f32_e32 v8, v8, v9
	v_add_f32_e32 v10, v10, v11
	v_add_f32_e32 v12, v12, v13
	v_add_f32_e32 v14, v14, v15
	v_add_f32_e32 v8, v8, v10
	v_mfma_f32_32x32x16_bf16 v[34:49], v[232:235], v[186:189], v[34:49]
	v_add_f32_e32 v12, v12, v14
	v_add_f32_e32 v8, v8, v12
	v_add_f32_e32 v203, v203, v8
	v_cndmask_b32_e64 v182, v182, 0, s[6:7]
	v_cndmask_b32_e64 v183, v183, 0, s[6:7]
	v_cndmask_b32_e64 v184, v184, 0, s[6:7]
	v_cndmask_b32_e64 v185, v185, 0, s[6:7]
	v_exp_f32_e32 v8, v66
	v_mfma_f32_32x32x16_bf16 v[18:33], v[236:239], v[190:193], v[18:33]
	v_exp_f32_e32 v9, v67
	v_exp_f32_e32 v10, v68
	v_exp_f32_e32 v11, v69
	v_exp_f32_e32 v12, v70
	v_exp_f32_e32 v13, v71
	v_exp_f32_e32 v14, v72
	v_exp_f32_e32 v15, v73
	v_cvt_pk_bf16_f32 v186, v8, v9
	v_mfma_f32_32x32x16_bf16 v[34:49], v[4:7], v[190:193], v[34:49]
	v_cvt_pk_bf16_f32 v187, v10, v11
	v_cvt_pk_bf16_f32 v188, v12, v13
	v_cvt_pk_bf16_f32 v189, v14, v15
	v_add_f32_e32 v8, v8, v9
	v_add_f32_e32 v10, v10, v11
	v_add_f32_e32 v12, v12, v13
	v_add_f32_e32 v14, v14, v15
	v_add_f32_e32 v8, v8, v10
	v_mfma_f32_32x32x16_bf16 v[18:33], v[146:149], v[178:181], v[18:33]
	v_add_f32_e32 v12, v12, v14
	v_add_f32_e32 v8, v8, v12
	v_add_f32_e32 v203, v203, v8
	v_cndmask_b32_e64 v186, v186, 0, s[6:7]
	v_cndmask_b32_e64 v187, v187, 0, s[6:7]
	v_cndmask_b32_e64 v188, v188, 0, s[6:7]
	v_cndmask_b32_e64 v189, v189, 0, s[6:7]
	v_exp_f32_e32 v8, v74
	v_mfma_f32_32x32x16_bf16 v[34:49], v[150:153], v[178:181], v[34:49]
	v_exp_f32_e32 v9, v75
	v_exp_f32_e32 v10, v76
	v_exp_f32_e32 v11, v77
	v_exp_f32_e32 v12, v78
	v_exp_f32_e32 v13, v79
	v_exp_f32_e32 v14, v80
	v_exp_f32_e32 v15, v81
	v_cvt_pk_bf16_f32 v190, v8, v9
	s_waitcnt lgkmcnt(10)
	v_mfma_f32_32x32x16_bf16 v[18:33], v[154:157], v[182:185], v[18:33]
	v_cvt_pk_bf16_f32 v191, v10, v11
	v_cvt_pk_bf16_f32 v192, v12, v13
	v_cvt_pk_bf16_f32 v193, v14, v15
	v_add_f32_e32 v8, v8, v9
	v_add_f32_e32 v10, v10, v11
	v_add_f32_e32 v12, v12, v13
	v_add_f32_e32 v14, v14, v15
	v_add_f32_e32 v8, v8, v10
	s_waitcnt lgkmcnt(8)
	v_mfma_f32_32x32x16_bf16 v[34:49], v[158:161], v[182:185], v[34:49]
	v_add_f32_e32 v12, v12, v14
	v_add_f32_e32 v8, v8, v12
	v_add_f32_e32 v203, v203, v8
	v_cndmask_b32_e64 v190, v190, 0, s[6:7]
	v_cndmask_b32_e64 v191, v191, 0, s[6:7]
	v_cndmask_b32_e64 v192, v192, 0, s[6:7]
	v_cndmask_b32_e64 v193, v193, 0, s[6:7]
	v_cndmask_b32_e64 v202, v202, 0, vcc
	s_waitcnt lgkmcnt(6)
	v_mfma_f32_32x32x16_bf16 v[18:33], v[162:165], v[186:189], v[18:33]
	v_cndmask_b32_e64 v203, v203, 0, s[6:7]
	v_add_f32_e32 v202, v202, v203
	v_add_f32_e32 v252, v2, v202
	s_waitcnt lgkmcnt(4)
	v_mfma_f32_32x32x16_bf16 v[34:49], v[166:169], v[186:189], v[34:49]
	v_mov_b32_e32 v2, v252
	v_mov_b32_e32 v4, v252
	s_nop 1
	s_waitcnt lgkmcnt(2)
	v_mfma_f32_32x32x16_bf16 v[18:33], v[170:173], v[190:193], v[18:33]
	v_permlane32_swap_b32_e32 v2, v4
	v_max_f32_e32 v4, v4, v4
	s_waitcnt lgkmcnt(0)
	v_mfma_f32_32x32x16_bf16 v[34:49], v[174:177], v[190:193], v[34:49]
	v_max_f32_e32 v2, v2, v2
	v_max_f32_e32 v2, v2, v4
	v_cmp_lt_f32_e32 vcc, s15, v2
	s_cbranch_vccz .LBB0_1333
.Lsel_shift:
	s_nop 0
	v_cndmask_b32_e32 v4, 0, v248, vcc
	v_cndmask_b32_e32 v2, 1.0, v249, vcc
	v_add_f32_e32 v243, v243, v4
	v_mul_f32_e32 v252, v252, v2
	v_pk_mul_f32 v[32:33], v[32:33], v[2:3] op_sel_hi:[1,0]
	v_pk_mul_f32 v[30:31], v[30:31], v[2:3] op_sel_hi:[1,0]
	v_pk_mul_f32 v[28:29], v[28:29], v[2:3] op_sel_hi:[1,0]
	v_pk_mul_f32 v[26:27], v[26:27], v[2:3] op_sel_hi:[1,0]
	v_pk_mul_f32 v[24:25], v[24:25], v[2:3] op_sel_hi:[1,0]
	v_pk_mul_f32 v[22:23], v[22:23], v[2:3] op_sel_hi:[1,0]
	v_pk_mul_f32 v[20:21], v[20:21], v[2:3] op_sel_hi:[1,0]
	v_pk_mul_f32 v[18:19], v[18:19], v[2:3] op_sel_hi:[1,0]
	v_pk_mul_f32 v[48:49], v[48:49], v[2:3] op_sel_hi:[1,0]
	v_pk_mul_f32 v[46:47], v[46:47], v[2:3] op_sel_hi:[1,0]
	v_pk_mul_f32 v[44:45], v[44:45], v[2:3] op_sel_hi:[1,0]
	v_pk_mul_f32 v[42:43], v[42:43], v[2:3] op_sel_hi:[1,0]
	v_pk_mul_f32 v[40:41], v[40:41], v[2:3] op_sel_hi:[1,0]
	v_pk_mul_f32 v[38:39], v[38:39], v[2:3] op_sel_hi:[1,0]
	v_pk_mul_f32 v[36:37], v[36:37], v[2:3] op_sel_hi:[1,0]
	v_pk_mul_f32 v[34:35], v[34:35], v[2:3] op_sel_hi:[1,0]
